# g1: step-B q/k gated-copy stores and step-E U^T stores widened to 16 B per lane via quad DPP / permlane32 / permlane16 exchanges (on top of scan U^T load widening)
# speedup vs baseline: 1.0464x; 1.0052x over previous
.LBB0_537:
	v_readfirstlane_b32 s100, v214
	s_mov_b32 s98, 0xcccccccc
	s_cmpk_lt_u32 s100, 0x80
	s_cselect_b32 s100, 1, 5
	s_mov_b32 s99, s98
	v_lshrrev_b32_e32 v254, s100, v214
	v_and_b32_e32 v254, 1, v254
	v_lshlrev_b32_e32 v254, 3, v254
	v_mov_b32_e32 v255, 0
	s_cmpk_gt_i32 s95, 0xfff
	s_cselect_b64 s[14:15], -1, 0
	s_mov_b64 s[10:11], -1
	s_and_b64 vcc, exec, s[14:15]
	s_cbranch_vccnz .LBB0_539
	s_ashr_i32 s75, s95, 10
	s_and_b32 s58, s95, 0x7f
	s_lshl_b32 s10, s75, 13
	s_lshl_b32 s11, s58, 6
	s_lshr_b32 s13, s95, 7
	s_or_b32 s12, s10, s11
	s_cmp_lg_u32 s58, 0
	s_mov_b64 s[10:11], 0
	s_cselect_b64 s[88:89], -1, 0

.LBB0_721:
	s_or_saveexec_b64 s[62:63], s[62:63]
	v_lshlrev_b32_e32 v46, 4, v101
	v_and_b32_e32 v49, 16, v46
	v_lshlrev_b32_e32 v46, 1, v101
	v_and_b32_e32 v48, 4, v46
	v_and_b32_e32 v50, 0x60, v161
	s_xor_b64 exec, exec, s[62:63]
	s_cbranch_execz .LBB0_723
	s_add_i32 s58, 0, 0x19d00
	v_lshl_add_u32 v46, v160, 2, s58
	v_mul_f32_e32 v52, 0x3db504f3, v148
	v_pk_mov_b32 v[54:55], v[118:119], v[104:105] op_sel:[1,0]
	ds_read_b32 v46, v46 offset:512
	v_pk_mul_f32 v[56:57], v[52:53], v[54:55] op_sel_hi:[0,1]
	v_pk_mov_b32 v[54:55], v[104:105], v[96:97] op_sel:[1,0]
	s_movk_i32 s58, 0x880
	v_pk_mul_f32 v[58:59], v[52:53], v[54:55] op_sel_hi:[0,1]
	v_pk_mov_b32 v[54:55], v[96:97], v[98:99] op_sel:[1,0]
	v_mad_u32_u24 v47, v232, s58, v60
	v_pk_mul_f32 v[62:63], v[52:53], v[54:55] op_sel_hi:[0,1]
	v_pk_mov_b32 v[54:55], v[98:99], v[118:119] op_sel:[1,0]
	s_add_u32 s58, s22, s64
	v_pk_mul_f32 v[64:65], v[52:53], v[54:55] op_sel_hi:[0,1]
	v_cvt_pk_bf16_f32 v52, v56, v57
	v_cvt_pk_bf16_f32 v53, v58, v59
	v_cvt_pk_bf16_f32 v54, v62, v63
	v_cvt_pk_bf16_f32 v55, v64, v65
	ds_write_b128 v47, v[52:55]
	s_waitcnt lgkmcnt(1)
	v_pk_mul_f32 v[52:53], v[56:57], v[46:47] op_sel_hi:[1,0]
	v_pk_mul_f32 v[54:55], v[58:59], v[46:47] op_sel_hi:[1,0]
	v_cvt_pk_bf16_f32 v52, v52, v53
	v_cvt_pk_bf16_f32 v53, v54, v55
	v_pk_mul_f32 v[54:55], v[62:63], v[46:47] op_sel_hi:[1,0]
	v_pk_mul_f32 v[46:47], v[64:65], v[46:47] op_sel_hi:[1,0]
	v_cvt_pk_bf16_f32 v54, v54, v55
	v_cvt_pk_bf16_f32 v55, v46, v47
	v_lshlrev_b32_e32 v46, 11, v137
	v_add3_u32 v47, v50, v49, v48
	v_lshl_or_b32 v172, v47, 1, v46
	s_addc_u32 s59, s23, s65
	v_lshl_add_u64 v[46:47], s[58:59], 0, v[172:173]
	v_add_co_u32_e32 v46, vcc, 0x16f89000, v46
	s_nop 1
	v_addc_co_u32_e32 v47, vcc, 0, v47, vcc
	s_mov_b64 vcc, s[98:99]
	s_nop 1
	v_mov_b32_dpp v253, v54 quad_perm:[2,3,0,1] row_mask:0xf bank_mask:0xf
	v_cndmask_b32_dpp v54, v52, v54, vcc quad_perm:[2,3,0,1] row_mask:0xf bank_mask:0xf
	v_cndmask_b32_e32 v52, v52, v253, vcc
	v_mov_b32_dpp v253, v55 quad_perm:[2,3,0,1] row_mask:0xf bank_mask:0xf
	v_cndmask_b32_dpp v55, v53, v55, vcc quad_perm:[2,3,0,1] row_mask:0xf bank_mask:0xf
	v_cndmask_b32_e32 v53, v53, v253, vcc
	v_lshl_add_u64 v[46:47], v[254:255], 0, v[46:47]
	global_store_dwordx4 v[46:47], v[52:55], off offset:256
	s_nop 1

.LBB0_727:
	s_or_saveexec_b64 s[62:63], s[62:63]
	v_add_u32_e32 v49, v50, v49
	v_lshlrev_b32_e32 v61, 7, v101
	v_add_lshl_u32 v62, v49, v48, 1
	s_xor_b64 exec, exec, s[62:63]
	s_cbranch_execz .LBB0_729
	s_add_i32 s58, 0, 0x19d00
	v_lshl_add_u32 v48, v51, 2, s58
	v_mul_f32_e32 v50, 0x3db504f3, v146
	v_pk_mov_b32 v[52:53], v[124:125], v[92:93] op_sel:[1,0]
	ds_read_b32 v48, v48 offset:512
	v_pk_mul_f32 v[56:57], v[50:51], v[52:53] op_sel_hi:[0,1]
	v_pk_mov_b32 v[52:53], v[92:93], v[88:89] op_sel:[1,0]
	s_movk_i32 s58, 0x110
	v_pk_mul_f32 v[58:59], v[50:51], v[52:53] op_sel_hi:[0,1]
	v_pk_mov_b32 v[52:53], v[88:89], v[90:91] op_sel:[1,0]
	v_mad_u32_u24 v49, v51, s58, v60
	v_pk_mul_f32 v[64:65], v[50:51], v[52:53] op_sel_hi:[0,1]
	v_pk_mov_b32 v[52:53], v[90:91], v[124:125] op_sel:[1,0]
	v_cvt_pk_bf16_f32 v54, v64, v65
	v_pk_mul_f32 v[66:67], v[50:51], v[52:53] op_sel_hi:[0,1]
	v_cvt_pk_bf16_f32 v52, v56, v57
	v_cvt_pk_bf16_f32 v53, v58, v59
	v_cvt_pk_bf16_f32 v55, v66, v67
	s_movk_i32 s58, 0x3800
	ds_write_b128 v49, v[52:55]
	s_waitcnt lgkmcnt(1)
	v_pk_mul_f32 v[50:51], v[56:57], v[48:49] op_sel_hi:[1,0]
	v_pk_mul_f32 v[52:53], v[58:59], v[48:49] op_sel_hi:[1,0]
	v_and_or_b32 v172, v61, s58, v62
	s_add_u32 s58, s22, s64
	v_cvt_pk_bf16_f32 v50, v50, v51
	v_cvt_pk_bf16_f32 v51, v52, v53
	v_pk_mul_f32 v[52:53], v[64:65], v[48:49] op_sel_hi:[1,0]
	v_pk_mul_f32 v[48:49], v[66:67], v[48:49] op_sel_hi:[1,0]
	s_addc_u32 s59, s23, s65
	v_cvt_pk_bf16_f32 v52, v52, v53
	v_cvt_pk_bf16_f32 v53, v48, v49
	v_lshl_add_u64 v[48:49], s[58:59], 0, v[172:173]
	v_add_co_u32_e32 v48, vcc, 0x16f89000, v48
	s_nop 1
	v_addc_co_u32_e32 v49, vcc, 0, v49, vcc
	s_mov_b64 vcc, s[98:99]
	s_nop 1
	v_mov_b32_dpp v253, v52 quad_perm:[2,3,0,1] row_mask:0xf bank_mask:0xf
	v_cndmask_b32_dpp v52, v50, v52, vcc quad_perm:[2,3,0,1] row_mask:0xf bank_mask:0xf
	v_cndmask_b32_e32 v50, v50, v253, vcc
	v_mov_b32_dpp v253, v53 quad_perm:[2,3,0,1] row_mask:0xf bank_mask:0xf
	v_cndmask_b32_dpp v53, v51, v53, vcc quad_perm:[2,3,0,1] row_mask:0xf bank_mask:0xf
	v_cndmask_b32_e32 v51, v51, v253, vcc
	v_lshl_add_u64 v[48:49], v[254:255], 0, v[48:49]
	global_store_dwordx4 v[48:49], v[50:53], off offset:512
	s_nop 1

.LBB0_733:
	s_andn2_saveexec_b64 s[62:63], s[62:63]
	s_cbranch_execz .LBB0_735
	s_add_i32 s58, 0, 0x19d00
	v_lshl_add_u32 v51, v50, 2, s58
	v_mul_f32_e32 v52, 0x3db504f3, v144
	v_pk_mov_b32 v[54:55], v[128:129], v[84:85] op_sel:[1,0]
	ds_read_b32 v56, v51 offset:512
	v_pk_mul_f32 v[58:59], v[52:53], v[54:55] op_sel_hi:[0,1]
	v_pk_mov_b32 v[54:55], v[84:85], v[80:81] op_sel:[1,0]
	s_movk_i32 s58, 0x110
	v_pk_mul_f32 v[64:65], v[52:53], v[54:55] op_sel_hi:[0,1]
	v_pk_mov_b32 v[54:55], v[80:81], v[82:83] op_sel:[1,0]
	v_mad_u32_u24 v50, v50, s58, v60
	v_pk_mul_f32 v[66:67], v[52:53], v[54:55] op_sel_hi:[0,1]
	v_pk_mov_b32 v[54:55], v[82:83], v[128:129] op_sel:[1,0]
	s_movk_i32 s58, 0x3800
	v_pk_mul_f32 v[68:69], v[52:53], v[54:55] op_sel_hi:[0,1]
	v_cvt_pk_bf16_f32 v52, v58, v59
	v_cvt_pk_bf16_f32 v53, v64, v65
	v_cvt_pk_bf16_f32 v54, v66, v67
	v_cvt_pk_bf16_f32 v55, v68, v69
	ds_write_b128 v50, v[52:55]
	s_waitcnt lgkmcnt(1)
	v_pk_mul_f32 v[50:51], v[58:59], v[56:57] op_sel_hi:[1,0]
	v_pk_mul_f32 v[52:53], v[64:65], v[56:57] op_sel_hi:[1,0]
	v_and_or_b32 v172, v61, s58, v62
	s_add_u32 s58, s22, s64
	v_cvt_pk_bf16_f32 v50, v50, v51
	v_cvt_pk_bf16_f32 v51, v52, v53
	v_pk_mul_f32 v[52:53], v[66:67], v[56:57] op_sel_hi:[1,0]
	v_pk_mul_f32 v[54:55], v[68:69], v[56:57] op_sel_hi:[1,0]
	s_addc_u32 s59, s23, s65
	v_cvt_pk_bf16_f32 v52, v52, v53
	v_cvt_pk_bf16_f32 v53, v54, v55
	v_lshl_add_u64 v[54:55], s[58:59], 0, v[172:173]
	v_add_co_u32_e32 v54, vcc, 0x16f89000, v54
	s_nop 1
	v_addc_co_u32_e32 v55, vcc, 0, v55, vcc
	s_mov_b64 vcc, s[98:99]
	s_nop 1
	v_mov_b32_dpp v253, v52 quad_perm:[2,3,0,1] row_mask:0xf bank_mask:0xf
	v_cndmask_b32_dpp v52, v50, v52, vcc quad_perm:[2,3,0,1] row_mask:0xf bank_mask:0xf
	v_cndmask_b32_e32 v50, v50, v253, vcc
	v_mov_b32_dpp v253, v53 quad_perm:[2,3,0,1] row_mask:0xf bank_mask:0xf
	v_cndmask_b32_dpp v53, v51, v53, vcc quad_perm:[2,3,0,1] row_mask:0xf bank_mask:0xf
	v_cndmask_b32_e32 v51, v51, v253, vcc
	v_lshl_add_u64 v[54:55], v[254:255], 0, v[54:55]
	global_store_dwordx4 v[54:55], v[50:53], off offset:768
	s_nop 1

.LBB0_739:
	s_andn2_saveexec_b64 s[62:63], s[62:63]
	s_cbranch_execz .LBB0_741
	s_add_i32 s58, 0, 0x19d00
	v_lshl_add_u32 v53, v52, 2, s58
	v_mul_f32_e32 v54, 0x3db504f3, v142
	v_pk_mov_b32 v[56:57], v[134:135], v[76:77] op_sel:[1,0]
	ds_read_b32 v58, v53 offset:512
	v_pk_mul_f32 v[64:65], v[54:55], v[56:57] op_sel_hi:[0,1]
	v_pk_mov_b32 v[56:57], v[76:77], v[78:79] op_sel:[1,0]
	s_movk_i32 s58, 0x110
	v_pk_mul_f32 v[66:67], v[54:55], v[56:57] op_sel_hi:[0,1]
	v_pk_mov_b32 v[56:57], v[78:79], v[86:87] op_sel:[1,0]
	v_mad_u32_u24 v52, v52, s58, v60
	v_pk_mul_f32 v[68:69], v[54:55], v[56:57] op_sel_hi:[0,1]
	v_pk_mov_b32 v[56:57], v[86:87], v[134:135] op_sel:[1,0]
	s_movk_i32 s58, 0x3800
	v_pk_mul_f32 v[70:71], v[54:55], v[56:57] op_sel_hi:[0,1]
	v_cvt_pk_bf16_f32 v54, v64, v65
	v_cvt_pk_bf16_f32 v55, v66, v67
	v_cvt_pk_bf16_f32 v56, v68, v69
	v_cvt_pk_bf16_f32 v57, v70, v71
	ds_write_b128 v52, v[54:57]
	s_waitcnt lgkmcnt(1)
	v_pk_mul_f32 v[52:53], v[64:65], v[58:59] op_sel_hi:[1,0]
	v_pk_mul_f32 v[54:55], v[66:67], v[58:59] op_sel_hi:[1,0]
	v_and_or_b32 v172, v61, s58, v62
	s_add_u32 s58, s22, s64
	v_cvt_pk_bf16_f32 v52, v52, v53
	v_cvt_pk_bf16_f32 v53, v54, v55
	v_pk_mul_f32 v[54:55], v[68:69], v[58:59] op_sel_hi:[1,0]
	v_pk_mul_f32 v[56:57], v[70:71], v[58:59] op_sel_hi:[1,0]
	s_addc_u32 s59, s23, s65
	v_cvt_pk_bf16_f32 v54, v54, v55
	v_cvt_pk_bf16_f32 v55, v56, v57
	v_lshl_add_u64 v[56:57], s[58:59], 0, v[172:173]
	v_add_co_u32_e32 v56, vcc, 0x16f89000, v56
	s_nop 1
	v_addc_co_u32_e32 v57, vcc, 0, v57, vcc
	s_mov_b64 vcc, s[98:99]
	s_nop 1
	v_mov_b32_dpp v253, v54 quad_perm:[2,3,0,1] row_mask:0xf bank_mask:0xf
	v_cndmask_b32_dpp v54, v52, v54, vcc quad_perm:[2,3,0,1] row_mask:0xf bank_mask:0xf
	v_cndmask_b32_e32 v52, v52, v253, vcc
	v_mov_b32_dpp v253, v55 quad_perm:[2,3,0,1] row_mask:0xf bank_mask:0xf
	v_cndmask_b32_dpp v55, v53, v55, vcc quad_perm:[2,3,0,1] row_mask:0xf bank_mask:0xf
	v_cndmask_b32_e32 v53, v53, v253, vcc
	v_lshl_add_u64 v[56:57], v[254:255], 0, v[56:57]
	global_store_dwordx4 v[56:57], v[52:55], off offset:1024
	s_nop 1

.LBB0_745:
	s_andn2_saveexec_b64 s[62:63], s[62:63]
	s_cbranch_execz .LBB0_747
	s_add_i32 s58, 0, 0x19d00
	v_lshl_add_u32 v55, v54, 2, s58
	v_mul_f32_e32 v56, 0x3db504f3, v140
	v_pk_mov_b32 v[58:59], v[152:153], v[94:95] op_sel:[1,0]
	ds_read_b32 v64, v55 offset:512
	v_pk_mul_f32 v[66:67], v[56:57], v[58:59] op_sel_hi:[0,1]
	v_pk_mov_b32 v[58:59], v[94:95], v[106:107] op_sel:[1,0]
	s_movk_i32 s58, 0x110
	v_pk_mul_f32 v[68:69], v[56:57], v[58:59] op_sel_hi:[0,1]
	v_pk_mov_b32 v[58:59], v[106:107], v[108:109] op_sel:[1,0]
	v_mad_u32_u24 v54, v54, s58, v60
	v_pk_mul_f32 v[70:71], v[56:57], v[58:59] op_sel_hi:[0,1]
	v_pk_mov_b32 v[58:59], v[108:109], v[152:153] op_sel:[1,0]
	s_movk_i32 s58, 0x3800
	v_pk_mul_f32 v[72:73], v[56:57], v[58:59] op_sel_hi:[0,1]
	v_cvt_pk_bf16_f32 v56, v66, v67
	v_cvt_pk_bf16_f32 v57, v68, v69
	v_cvt_pk_bf16_f32 v58, v70, v71
	v_cvt_pk_bf16_f32 v59, v72, v73
	ds_write_b128 v54, v[56:59]
	s_waitcnt lgkmcnt(1)
	v_pk_mul_f32 v[54:55], v[66:67], v[64:65] op_sel_hi:[1,0]
	v_pk_mul_f32 v[56:57], v[68:69], v[64:65] op_sel_hi:[1,0]
	v_and_or_b32 v172, v61, s58, v62
	s_add_u32 s58, s22, s64
	v_cvt_pk_bf16_f32 v54, v54, v55
	v_cvt_pk_bf16_f32 v55, v56, v57
	v_pk_mul_f32 v[56:57], v[70:71], v[64:65] op_sel_hi:[1,0]
	v_pk_mul_f32 v[58:59], v[72:73], v[64:65] op_sel_hi:[1,0]
	s_addc_u32 s59, s23, s65
	v_cvt_pk_bf16_f32 v56, v56, v57
	v_cvt_pk_bf16_f32 v57, v58, v59
	v_lshl_add_u64 v[58:59], s[58:59], 0, v[172:173]
	v_add_co_u32_e32 v58, vcc, 0x16f89000, v58
	s_nop 1
	v_addc_co_u32_e32 v59, vcc, 0, v59, vcc
	s_mov_b64 vcc, s[98:99]
	s_nop 1
	v_mov_b32_dpp v253, v56 quad_perm:[2,3,0,1] row_mask:0xf bank_mask:0xf
	v_cndmask_b32_dpp v56, v54, v56, vcc quad_perm:[2,3,0,1] row_mask:0xf bank_mask:0xf
	v_cndmask_b32_e32 v54, v54, v253, vcc
	v_mov_b32_dpp v253, v57 quad_perm:[2,3,0,1] row_mask:0xf bank_mask:0xf
	v_cndmask_b32_dpp v57, v55, v57, vcc quad_perm:[2,3,0,1] row_mask:0xf bank_mask:0xf
	v_cndmask_b32_e32 v55, v55, v253, vcc
	v_lshl_add_u64 v[58:59], v[254:255], 0, v[58:59]
	global_store_dwordx4 v[58:59], v[54:57], off offset:1280
	s_nop 1

.LBB0_751:
	s_andn2_saveexec_b64 s[62:63], s[62:63]
	s_cbranch_execz .LBB0_753
	s_add_i32 s58, 0, 0x19d00
	v_lshl_add_u32 v57, v56, 2, s58
	v_mul_f32_e32 v64, 0x3db504f3, v138
	v_pk_mov_b32 v[66:67], v[154:155], v[110:111] op_sel:[1,0]
	ds_read_b32 v58, v57 offset:512
	v_pk_mul_f32 v[68:69], v[64:65], v[66:67] op_sel_hi:[0,1]
	v_pk_mov_b32 v[66:67], v[110:111], v[112:113] op_sel:[1,0]
	s_movk_i32 s58, 0x110
	v_pk_mul_f32 v[70:71], v[64:65], v[66:67] op_sel_hi:[0,1]
	v_pk_mov_b32 v[66:67], v[112:113], v[114:115] op_sel:[1,0]
	v_mad_u32_u24 v56, v56, s58, v60
	v_pk_mul_f32 v[72:73], v[64:65], v[66:67] op_sel_hi:[0,1]
	v_pk_mov_b32 v[66:67], v[114:115], v[154:155] op_sel:[1,0]
	s_movk_i32 s58, 0x3800
	v_pk_mul_f32 v[74:75], v[64:65], v[66:67] op_sel_hi:[0,1]
	v_cvt_pk_bf16_f32 v64, v68, v69
	v_cvt_pk_bf16_f32 v65, v70, v71
	v_cvt_pk_bf16_f32 v66, v72, v73
	v_cvt_pk_bf16_f32 v67, v74, v75
	ds_write_b128 v56, v[64:67]
	s_waitcnt lgkmcnt(1)
	v_pk_mul_f32 v[56:57], v[68:69], v[58:59] op_sel_hi:[1,0]
	v_pk_mul_f32 v[64:65], v[70:71], v[58:59] op_sel_hi:[1,0]
	v_and_or_b32 v172, v61, s58, v62
	s_add_u32 s58, s22, s64
	v_cvt_pk_bf16_f32 v56, v56, v57
	v_cvt_pk_bf16_f32 v57, v64, v65
	v_pk_mul_f32 v[64:65], v[72:73], v[58:59] op_sel_hi:[1,0]
	v_pk_mul_f32 v[58:59], v[74:75], v[58:59] op_sel_hi:[1,0]
	s_addc_u32 s59, s23, s65
	v_cvt_pk_bf16_f32 v64, v64, v65
	v_cvt_pk_bf16_f32 v65, v58, v59
	v_lshl_add_u64 v[58:59], s[58:59], 0, v[172:173]
	v_add_co_u32_e32 v58, vcc, 0x16f89000, v58
	s_nop 1
	v_addc_co_u32_e32 v59, vcc, 0, v59, vcc
	v_mov_b32_e32 v66, v64
	v_mov_b32_e32 v67, v65
	v_mov_b32_e32 v64, v56
	v_mov_b32_e32 v65, v57
	s_mov_b64 vcc, s[98:99]
	s_nop 1
	v_mov_b32_dpp v253, v66 quad_perm:[2,3,0,1] row_mask:0xf bank_mask:0xf
	v_cndmask_b32_dpp v66, v64, v66, vcc quad_perm:[2,3,0,1] row_mask:0xf bank_mask:0xf
	v_cndmask_b32_e32 v64, v64, v253, vcc
	v_mov_b32_dpp v253, v67 quad_perm:[2,3,0,1] row_mask:0xf bank_mask:0xf
	v_cndmask_b32_dpp v67, v65, v67, vcc quad_perm:[2,3,0,1] row_mask:0xf bank_mask:0xf
	v_cndmask_b32_e32 v65, v65, v253, vcc
	v_lshl_add_u64 v[58:59], v[254:255], 0, v[58:59]
	global_store_dwordx4 v[58:59], v[64:67], off offset:1536
	s_nop 1

.LBB0_757:
	s_andn2_saveexec_b64 s[62:63], s[62:63]
	s_cbranch_execz .LBB0_759
	s_add_i32 s58, 0, 0x19d00
	v_lshl_add_u32 v59, v58, 2, s58
	v_mul_f32_e32 v64, 0x3db504f3, v136
	v_pk_mov_b32 v[66:67], v[156:157], v[116:117] op_sel:[1,0]
	ds_read_b32 v68, v59 offset:512
	v_pk_mul_f32 v[70:71], v[64:65], v[66:67] op_sel_hi:[0,1]
	v_pk_mov_b32 v[66:67], v[116:117], v[120:121] op_sel:[1,0]
	s_movk_i32 s58, 0x110
	v_pk_mul_f32 v[72:73], v[64:65], v[66:67] op_sel_hi:[0,1]
	v_pk_mov_b32 v[66:67], v[120:121], v[122:123] op_sel:[1,0]
	v_mad_u32_u24 v58, v58, s58, v60
	v_pk_mul_f32 v[74:75], v[64:65], v[66:67] op_sel_hi:[0,1]
	v_pk_mov_b32 v[66:67], v[122:123], v[156:157] op_sel:[1,0]
	s_movk_i32 s58, 0x3800
	v_pk_mul_f32 v[118:119], v[64:65], v[66:67] op_sel_hi:[0,1]
	v_cvt_pk_bf16_f32 v64, v70, v71
	v_cvt_pk_bf16_f32 v65, v72, v73
	v_cvt_pk_bf16_f32 v66, v74, v75
	v_cvt_pk_bf16_f32 v67, v118, v119
	ds_write_b128 v58, v[64:67]
	s_waitcnt lgkmcnt(1)
	v_pk_mul_f32 v[58:59], v[70:71], v[68:69] op_sel_hi:[1,0]
	v_pk_mul_f32 v[64:65], v[72:73], v[68:69] op_sel_hi:[1,0]
	v_and_or_b32 v172, v61, s58, v62
	s_add_u32 s58, s22, s64
	v_cvt_pk_bf16_f32 v58, v58, v59
	v_cvt_pk_bf16_f32 v59, v64, v65
	v_pk_mul_f32 v[64:65], v[74:75], v[68:69] op_sel_hi:[1,0]
	v_pk_mul_f32 v[66:67], v[118:119], v[68:69] op_sel_hi:[1,0]
	s_addc_u32 s59, s23, s65
	v_cvt_pk_bf16_f32 v64, v64, v65
	v_cvt_pk_bf16_f32 v65, v66, v67
	v_lshl_add_u64 v[66:67], s[58:59], 0, v[172:173]
	v_add_co_u32_e32 v66, vcc, 0x16f89000, v66
	s_nop 1
	v_addc_co_u32_e32 v67, vcc, 0, v67, vcc
	v_mov_b32_e32 v72, v58
	v_mov_b32_e32 v73, v59
	v_mov_b32_e32 v74, v64
	v_mov_b32_e32 v75, v65
	s_mov_b64 vcc, s[98:99]
	s_nop 1
	v_mov_b32_dpp v253, v74 quad_perm:[2,3,0,1] row_mask:0xf bank_mask:0xf
	v_cndmask_b32_dpp v74, v72, v74, vcc quad_perm:[2,3,0,1] row_mask:0xf bank_mask:0xf
	v_cndmask_b32_e32 v72, v72, v253, vcc
	v_mov_b32_dpp v253, v75 quad_perm:[2,3,0,1] row_mask:0xf bank_mask:0xf
	v_cndmask_b32_dpp v75, v73, v75, vcc quad_perm:[2,3,0,1] row_mask:0xf bank_mask:0xf
	v_cndmask_b32_e32 v73, v73, v253, vcc
	v_lshl_add_u64 v[66:67], v[254:255], 0, v[66:67]
	global_store_dwordx4 v[66:67], v[72:75], off offset:1792
	s_nop 1

.LBB0_765:
	s_add_i32 s58, 0, 0x19d00
	v_lshl_add_u32 v64, v63, 2, s58
	ds_read_b32 v68, v64 offset:512
	v_mul_f32_e32 v64, 0x3db504f3, v150
	v_pk_mov_b32 v[66:67], v[158:159], v[126:127] op_sel:[1,0]
	s_movk_i32 s58, 0x110
	v_pk_mul_f32 v[70:71], v[64:65], v[66:67] op_sel_hi:[0,1]
	v_pk_mov_b32 v[66:67], v[126:127], v[130:131] op_sel:[1,0]
	v_mad_u32_u24 v60, v63, s58, v60
	v_pk_mul_f32 v[72:73], v[64:65], v[66:67] op_sel_hi:[0,1]
	v_pk_mov_b32 v[66:67], v[130:131], v[132:133] op_sel:[1,0]
	s_movk_i32 s58, 0x3800
	v_pk_mul_f32 v[74:75], v[64:65], v[66:67] op_sel_hi:[0,1]
	v_pk_mov_b32 v[66:67], v[132:133], v[158:159] op_sel:[1,0]
	v_and_or_b32 v172, v61, s58, v62
	v_pk_mul_f32 v[118:119], v[64:65], v[66:67] op_sel_hi:[0,1]
	s_add_u32 s58, s22, s64
	v_cvt_pk_bf16_f32 v64, v70, v71
	v_cvt_pk_bf16_f32 v65, v72, v73
	v_cvt_pk_bf16_f32 v66, v74, v75
	v_cvt_pk_bf16_f32 v67, v118, v119
	s_addc_u32 s59, s23, s65
	ds_write_b128 v60, v[64:67]
	v_lshl_add_u64 v[60:61], s[58:59], 0, v[172:173]
	s_waitcnt lgkmcnt(1)
	v_pk_mul_f32 v[64:65], v[70:71], v[68:69] op_sel_hi:[1,0]
	v_pk_mul_f32 v[66:67], v[72:73], v[68:69] op_sel_hi:[1,0]
	v_add_co_u32_e32 v60, vcc, 0x16f89000, v60
	v_cvt_pk_bf16_f32 v64, v64, v65
	v_cvt_pk_bf16_f32 v65, v66, v67
	v_pk_mul_f32 v[66:67], v[74:75], v[68:69] op_sel_hi:[1,0]
	v_pk_mul_f32 v[68:69], v[118:119], v[68:69] op_sel_hi:[1,0]
	v_addc_co_u32_e32 v61, vcc, 0, v61, vcc
	v_cvt_pk_bf16_f32 v66, v66, v67
	v_cvt_pk_bf16_f32 v67, v68, v69
	s_mov_b64 vcc, s[98:99]
	s_nop 1
	v_mov_b32_dpp v253, v66 quad_perm:[2,3,0,1] row_mask:0xf bank_mask:0xf
	v_cndmask_b32_dpp v66, v64, v66, vcc quad_perm:[2,3,0,1] row_mask:0xf bank_mask:0xf
	v_cndmask_b32_e32 v64, v64, v253, vcc
	v_mov_b32_dpp v253, v67 quad_perm:[2,3,0,1] row_mask:0xf bank_mask:0xf
	v_cndmask_b32_dpp v67, v65, v67, vcc quad_perm:[2,3,0,1] row_mask:0xf bank_mask:0xf
	v_cndmask_b32_e32 v65, v65, v253, vcc
	v_lshl_add_u64 v[60:61], v[254:255], 0, v[60:61]
	global_store_dwordx4 v[60:61], v[64:67], off offset:2048
	s_nop 1
	s_or_b64 exec, exec, s[12:13]
	v_cmp_lt_i32_e32 vcc, 0, v233
	s_and_saveexec_b64 s[12:13], vcc
	s_cbranch_execz .LBB0_798

.LBB0_782:
	s_or_b64 exec, exec, s[62:63]
	v_mov_b32_e32 v152, v45
	v_mov_b32_e32 v153, v47
	v_pk_mul_f32 v[154:155], v[152:153], v[62:63]
	ds_read_b32 v135, v129 offset:796
	v_cvt_pk_bf16_f32 v162, v154, v155
	v_mov_b32_e32 v154, v49
	v_mov_b32_e32 v155, v51
	v_pk_mul_f32 v[156:157], v[154:155], v[70:71]
	v_lshl_add_u32 v66, v232, 4, v60
	v_cvt_pk_bf16_f32 v163, v156, v157
	v_mov_b32_e32 v156, v53
	v_mov_b32_e32 v157, v55
	v_pk_mul_f32 v[158:159], v[156:157], v[118:119]
	v_and_b32_e32 v60, 16, v101
	v_lshlrev_b32_e32 v64, 1, v137
	v_and_b32_e32 v68, 32, v160
	v_cvt_pk_bf16_f32 v164, v158, v159
	v_mov_b32_e32 v158, v57
	v_mov_b32_e32 v159, v59
	s_waitcnt lgkmcnt(1)
	v_mov_b32_e32 v129, v124
	v_and_b32_e32 v64, 4, v64
	v_pk_mul_f32 v[166:167], v[158:159], v[128:129]
	s_movk_i32 s58, 0x480
	v_add_u32_e32 v60, v68, v60
	v_cvt_pk_bf16_f32 v165, v166, v167
	v_mad_u32_u24 v72, v231, s58, v66
	v_add_lshl_u32 v60, v60, v64, 1
	ds_write_b128 v72, v[162:165]
	s_and_saveexec_b64 s[62:63], s[10:11]
	s_cbranch_execz .LBB0_784
	v_mov_b32_e32 v64, v61
	v_mov_b32_e32 v68, v67
	v_pk_mul_f32 v[152:153], v[152:153], v[64:65]
	v_pk_mul_f32 v[154:155], v[154:155], v[68:69]
	v_mov_b32_e32 v74, v73
	v_mov_b32_e32 v134, v125
	s_add_u32 s58, s22, s64
	v_cvt_pk_bf16_f32 v152, v152, v153
	v_cvt_pk_bf16_f32 v153, v154, v155
	v_pk_mul_f32 v[154:155], v[156:157], v[74:75]
	s_waitcnt lgkmcnt(1)
	v_pk_mul_f32 v[156:157], v[158:159], v[134:135]
	v_lshl_or_b32 v172, v231, 10, v60
	s_addc_u32 s59, s23, s65
	v_cvt_pk_bf16_f32 v154, v154, v155
	v_cvt_pk_bf16_f32 v155, v156, v157
	v_lshl_add_u64 v[156:157], s[58:59], 0, v[172:173]
	v_add_co_u32_e32 v156, vcc, 0x16f8d000, v156
	s_nop 1
	v_addc_co_u32_e32 v157, vcc, 0, v157, vcc
	s_nop 1
	v_permlane32_swap_b32_e32 v152, v154
	v_permlane32_swap_b32_e32 v153, v155
	v_lshl_add_u64 v[156:157], v[254:255], 0, v[156:157]
	global_store_dwordx4 v[156:157], v[152:155], off offset:256
	s_nop 1
.LBB0_784:
	s_or_b64 exec, exec, s[62:63]
	v_mov_b32_e32 v154, v104
	v_mov_b32_e32 v155, v92
	v_pk_mul_f32 v[152:153], v[154:155], v[62:63]
	v_mov_b32_e32 v158, v84
	v_mov_b32_e32 v159, v76
	v_cvt_pk_bf16_f32 v160, v152, v153
	v_pk_mul_f32 v[152:153], v[158:159], v[70:71]
	v_or_b32_e32 v72, 1, v161
	v_cvt_pk_bf16_f32 v161, v152, v153
	v_mov_b32_e32 v152, v94
	v_mov_b32_e32 v153, v110
	v_pk_mul_f32 v[156:157], v[152:153], v[118:119]
	s_movk_i32 s58, 0x90
	v_cvt_pk_bf16_f32 v162, v156, v157
	v_mov_b32_e32 v156, v116
	v_mov_b32_e32 v157, v126
	v_pk_mul_f32 v[164:165], v[156:157], v[128:129]
	v_mad_u32_u24 v64, v72, s58, v66
	v_cvt_pk_bf16_f32 v163, v164, v165
	ds_write_b128 v64, v[160:163]
	s_and_saveexec_b64 s[62:63], s[10:11]
	s_cbranch_execz .LBB0_786
	v_mov_b32_e32 v74, v73
	v_mov_b32_e32 v134, v125
	s_add_u32 s58, s22, s64
	v_pk_mul_f32 v[152:153], v[152:153], v[74:75]
	s_waitcnt lgkmcnt(2)
	v_pk_mul_f32 v[156:157], v[156:157], v[134:135]
	v_lshl_or_b32 v172, v231, 10, v60
	s_addc_u32 s59, s23, s65
	v_mov_b32_e32 v64, v61
	v_mov_b32_e32 v68, v67
	v_cvt_pk_bf16_f32 v152, v152, v153
	v_cvt_pk_bf16_f32 v153, v156, v157
	v_lshl_add_u64 v[156:157], s[58:59], 0, v[172:173]
	v_pk_mul_f32 v[154:155], v[154:155], v[64:65]
	v_pk_mul_f32 v[158:159], v[158:159], v[68:69]
	v_add_co_u32_e32 v156, vcc, 0x16f8d000, v156
	v_cvt_pk_bf16_f32 v154, v154, v155
	v_cvt_pk_bf16_f32 v155, v158, v159
	v_addc_co_u32_e32 v157, vcc, 0, v157, vcc
	v_swap_b32 v152, v154
	v_swap_b32 v153, v155
	s_nop 1
	v_permlane32_swap_b32_e32 v152, v154
	v_permlane32_swap_b32_e32 v153, v155
	v_lshl_add_u64 v[156:157], v[254:255], 0, v[156:157]
	global_store_dwordx4 v[156:157], v[152:155], off offset:384
	s_nop 1
.LBB0_786:
	s_or_b64 exec, exec, s[62:63]
	v_mov_b32_e32 v154, v105
	v_mov_b32_e32 v155, v93
	v_pk_mul_f32 v[152:153], v[154:155], v[62:63]
	v_mov_b32_e32 v158, v85
	v_mov_b32_e32 v159, v77
	v_cvt_pk_bf16_f32 v160, v152, v153
	v_pk_mul_f32 v[152:153], v[158:159], v[70:71]
	v_mul_u32_u24_e32 v64, 0x90, v72
	v_cvt_pk_bf16_f32 v161, v152, v153
	v_mov_b32_e32 v152, v95
	v_mov_b32_e32 v153, v111
	v_pk_mul_f32 v[156:157], v[152:153], v[118:119]
	v_add_u32_e32 v66, v64, v66
	v_cvt_pk_bf16_f32 v162, v156, v157
	v_mov_b32_e32 v156, v117
	v_mov_b32_e32 v157, v127
	v_pk_mul_f32 v[164:165], v[156:157], v[128:129]
	s_nop 0
	v_cvt_pk_bf16_f32 v163, v164, v165
	ds_write_b128 v66, v[160:163] offset:144
	s_and_saveexec_b64 s[62:63], s[10:11]
	s_cbranch_execz .LBB0_788
	v_mov_b32_e32 v74, v73
	v_mov_b32_e32 v134, v125
	s_add_u32 s58, s22, s64
	v_pk_mul_f32 v[152:153], v[152:153], v[74:75]
	s_waitcnt lgkmcnt(3)
	v_pk_mul_f32 v[156:157], v[156:157], v[134:135]
	v_lshl_or_b32 v172, v231, 10, v60
	s_addc_u32 s59, s23, s65
	v_mov_b32_e32 v64, v61
	v_mov_b32_e32 v68, v67
	v_cvt_pk_bf16_f32 v152, v152, v153
	v_cvt_pk_bf16_f32 v153, v156, v157
	v_lshl_add_u64 v[156:157], s[58:59], 0, v[172:173]
	v_pk_mul_f32 v[154:155], v[154:155], v[64:65]
	v_pk_mul_f32 v[158:159], v[158:159], v[68:69]
	v_add_co_u32_e32 v156, vcc, 0x16f8d000, v156
	v_cvt_pk_bf16_f32 v154, v154, v155
	v_cvt_pk_bf16_f32 v155, v158, v159
	v_addc_co_u32_e32 v157, vcc, 0, v157, vcc
	v_swap_b32 v152, v154
	v_swap_b32 v153, v155
	s_nop 1
	v_permlane32_swap_b32_e32 v152, v154
	v_permlane32_swap_b32_e32 v153, v155
	v_lshl_add_u64 v[156:157], v[254:255], 0, v[156:157]
	global_store_dwordx4 v[156:157], v[152:155], off offset:512
	s_nop 1
.LBB0_788:
	s_or_b64 exec, exec, s[62:63]
	v_mov_b32_e32 v154, v96
	v_mov_b32_e32 v155, v88
	v_pk_mul_f32 v[152:153], v[154:155], v[62:63]
	v_mov_b32_e32 v158, v80
	v_mov_b32_e32 v159, v78
	v_cvt_pk_bf16_f32 v160, v152, v153
	v_pk_mul_f32 v[152:153], v[158:159], v[70:71]
	s_nop 0
	v_cvt_pk_bf16_f32 v161, v152, v153
	v_mov_b32_e32 v152, v106
	v_mov_b32_e32 v153, v112
	v_pk_mul_f32 v[156:157], v[152:153], v[118:119]
	s_nop 0
	v_cvt_pk_bf16_f32 v162, v156, v157
	v_mov_b32_e32 v156, v120
	v_mov_b32_e32 v157, v130
	v_pk_mul_f32 v[164:165], v[156:157], v[128:129]
	s_nop 0
	v_cvt_pk_bf16_f32 v163, v164, v165
	ds_write_b128 v66, v[160:163] offset:288
	s_and_saveexec_b64 s[62:63], s[10:11]
	s_cbranch_execz .LBB0_790
	v_mov_b32_e32 v74, v73
	v_mov_b32_e32 v134, v125
	s_add_u32 s58, s22, s64
	v_pk_mul_f32 v[152:153], v[152:153], v[74:75]
	s_waitcnt lgkmcnt(4)
	v_pk_mul_f32 v[156:157], v[156:157], v[134:135]
	v_lshl_or_b32 v172, v231, 10, v60
	s_addc_u32 s59, s23, s65
	v_mov_b32_e32 v64, v61
	v_mov_b32_e32 v68, v67
	v_cvt_pk_bf16_f32 v152, v152, v153
	v_cvt_pk_bf16_f32 v153, v156, v157
	v_lshl_add_u64 v[156:157], s[58:59], 0, v[172:173]
	v_pk_mul_f32 v[154:155], v[154:155], v[64:65]
	v_pk_mul_f32 v[158:159], v[158:159], v[68:69]
	v_add_co_u32_e32 v156, vcc, 0x16f8d000, v156
	v_cvt_pk_bf16_f32 v154, v154, v155
	v_cvt_pk_bf16_f32 v155, v158, v159
	v_addc_co_u32_e32 v157, vcc, 0, v157, vcc
	v_swap_b32 v152, v154
	v_swap_b32 v153, v155
	s_nop 1
	v_permlane32_swap_b32_e32 v152, v154
	v_permlane32_swap_b32_e32 v153, v155
	v_lshl_add_u64 v[156:157], v[254:255], 0, v[156:157]
	global_store_dwordx4 v[156:157], v[152:155], off offset:640
	s_nop 1
.LBB0_790:
	s_or_b64 exec, exec, s[62:63]
	v_mov_b32_e32 v154, v97
	v_mov_b32_e32 v155, v89
	v_pk_mul_f32 v[152:153], v[154:155], v[62:63]
	v_mov_b32_e32 v158, v81
	v_mov_b32_e32 v159, v79
	v_cvt_pk_bf16_f32 v160, v152, v153
	v_pk_mul_f32 v[152:153], v[158:159], v[70:71]
	s_nop 0
	v_cvt_pk_bf16_f32 v161, v152, v153
	v_mov_b32_e32 v152, v107
	v_mov_b32_e32 v153, v113
	v_pk_mul_f32 v[156:157], v[152:153], v[118:119]
	s_nop 0
	v_cvt_pk_bf16_f32 v162, v156, v157
	v_mov_b32_e32 v156, v121
	v_mov_b32_e32 v157, v131
	v_pk_mul_f32 v[164:165], v[156:157], v[128:129]
	s_nop 0
	v_cvt_pk_bf16_f32 v163, v164, v165
	ds_write_b128 v66, v[160:163] offset:432
	s_and_saveexec_b64 s[62:63], s[10:11]
	s_cbranch_execz .LBB0_792
	v_mov_b32_e32 v74, v73
	v_mov_b32_e32 v134, v125
	s_add_u32 s58, s22, s64
	v_pk_mul_f32 v[152:153], v[152:153], v[74:75]
	s_waitcnt lgkmcnt(5)
	v_pk_mul_f32 v[156:157], v[156:157], v[134:135]
	v_lshl_or_b32 v172, v231, 10, v60
	s_addc_u32 s59, s23, s65
	v_mov_b32_e32 v64, v61
	v_mov_b32_e32 v68, v67
	v_cvt_pk_bf16_f32 v152, v152, v153
	v_cvt_pk_bf16_f32 v153, v156, v157
	v_lshl_add_u64 v[156:157], s[58:59], 0, v[172:173]
	v_pk_mul_f32 v[154:155], v[154:155], v[64:65]
	v_pk_mul_f32 v[158:159], v[158:159], v[68:69]
	v_add_co_u32_e32 v156, vcc, 0x16f8d000, v156
	v_cvt_pk_bf16_f32 v154, v154, v155
	v_cvt_pk_bf16_f32 v155, v158, v159
	v_addc_co_u32_e32 v157, vcc, 0, v157, vcc
	v_swap_b32 v152, v154
	v_swap_b32 v153, v155
	s_nop 1
	v_permlane32_swap_b32_e32 v152, v154
	v_permlane32_swap_b32_e32 v153, v155
	v_lshl_add_u64 v[156:157], v[254:255], 0, v[156:157]
	global_store_dwordx4 v[156:157], v[152:155], off offset:768
	s_nop 1
.LBB0_792:
	s_or_b64 exec, exec, s[62:63]
	v_mov_b32_e32 v154, v98
	v_mov_b32_e32 v155, v90
	v_pk_mul_f32 v[152:153], v[154:155], v[62:63]
	v_mov_b32_e32 v158, v82
	v_mov_b32_e32 v159, v86
	v_cvt_pk_bf16_f32 v160, v152, v153
	v_pk_mul_f32 v[152:153], v[158:159], v[70:71]
	s_nop 0
	v_cvt_pk_bf16_f32 v161, v152, v153
	v_mov_b32_e32 v152, v108
	v_mov_b32_e32 v153, v114
	v_pk_mul_f32 v[156:157], v[152:153], v[118:119]
	s_nop 0
	v_cvt_pk_bf16_f32 v162, v156, v157
	v_mov_b32_e32 v156, v122
	v_mov_b32_e32 v157, v132
	v_pk_mul_f32 v[164:165], v[156:157], v[128:129]
	s_nop 0
	v_cvt_pk_bf16_f32 v163, v164, v165
	ds_write_b128 v66, v[160:163] offset:576
	s_and_saveexec_b64 s[62:63], s[10:11]
	s_cbranch_execz .LBB0_794
	v_mov_b32_e32 v74, v73
	v_mov_b32_e32 v134, v125
	s_add_u32 s58, s22, s64
	v_pk_mul_f32 v[152:153], v[152:153], v[74:75]
	s_waitcnt lgkmcnt(6)
	v_pk_mul_f32 v[156:157], v[156:157], v[134:135]
	v_lshl_or_b32 v172, v231, 10, v60
	s_addc_u32 s59, s23, s65
	v_mov_b32_e32 v64, v61
	v_mov_b32_e32 v68, v67
	v_cvt_pk_bf16_f32 v152, v152, v153
	v_cvt_pk_bf16_f32 v153, v156, v157
	v_lshl_add_u64 v[156:157], s[58:59], 0, v[172:173]
	v_pk_mul_f32 v[154:155], v[154:155], v[64:65]
	v_pk_mul_f32 v[158:159], v[158:159], v[68:69]
	v_add_co_u32_e32 v156, vcc, 0x16f8d000, v156
	v_cvt_pk_bf16_f32 v154, v154, v155
	v_cvt_pk_bf16_f32 v155, v158, v159
	v_addc_co_u32_e32 v157, vcc, 0, v157, vcc
	v_swap_b32 v152, v154
	v_swap_b32 v153, v155
	s_nop 1
	v_permlane32_swap_b32_e32 v152, v154
	v_permlane32_swap_b32_e32 v153, v155
	v_lshl_add_u64 v[156:157], v[254:255], 0, v[156:157]
	global_store_dwordx4 v[156:157], v[152:155], off offset:896
	s_nop 1
.LBB0_794:
	s_or_b64 exec, exec, s[62:63]
	v_mov_b32_e32 v154, v99
	v_mov_b32_e32 v155, v91
	v_pk_mul_f32 v[152:153], v[154:155], v[62:63]
	v_mov_b32_e32 v158, v83
	v_mov_b32_e32 v159, v87
	v_cvt_pk_bf16_f32 v160, v152, v153
	v_pk_mul_f32 v[152:153], v[158:159], v[70:71]
	s_nop 0
	v_cvt_pk_bf16_f32 v161, v152, v153
	v_mov_b32_e32 v152, v109
	v_mov_b32_e32 v153, v115
	v_pk_mul_f32 v[156:157], v[152:153], v[118:119]
	s_nop 0
	v_cvt_pk_bf16_f32 v162, v156, v157
	v_mov_b32_e32 v156, v123
	v_mov_b32_e32 v157, v133
	v_pk_mul_f32 v[164:165], v[156:157], v[128:129]
	s_nop 0
	v_cvt_pk_bf16_f32 v163, v164, v165
	ds_write_b128 v66, v[160:163] offset:720
	s_and_saveexec_b64 s[62:63], s[10:11]
	s_cbranch_execz .LBB0_796
	v_mov_b32_e32 v74, v73
	v_mov_b32_e32 v134, v125
	s_add_u32 s58, s22, s64
	v_pk_mul_f32 v[152:153], v[152:153], v[74:75]
	s_waitcnt lgkmcnt(7)
	v_pk_mul_f32 v[156:157], v[156:157], v[134:135]
	v_lshl_or_b32 v172, v231, 10, v60
	s_addc_u32 s59, s23, s65
	v_mov_b32_e32 v64, v61
	v_mov_b32_e32 v68, v67
	v_cvt_pk_bf16_f32 v152, v152, v153
	v_cvt_pk_bf16_f32 v153, v156, v157
	v_lshl_add_u64 v[156:157], s[58:59], 0, v[172:173]
	v_pk_mul_f32 v[154:155], v[154:155], v[64:65]
	v_pk_mul_f32 v[158:159], v[158:159], v[68:69]
	v_add_co_u32_e32 v156, vcc, 0x16f8d000, v156
	v_cvt_pk_bf16_f32 v154, v154, v155
	v_cvt_pk_bf16_f32 v155, v158, v159
	v_addc_co_u32_e32 v157, vcc, 0, v157, vcc
	v_swap_b32 v152, v154
	v_swap_b32 v153, v155
	s_nop 1
	v_permlane32_swap_b32_e32 v152, v154
	v_permlane32_swap_b32_e32 v153, v155
	v_lshl_add_u64 v[156:157], v[254:255], 0, v[156:157]
	global_store_dwordx4 v[156:157], v[152:155], off offset:1024
	s_nop 1
.LBB0_796:
	s_or_b64 exec, exec, s[62:63]
	v_mov_b32_e32 v152, v44
	v_mov_b32_e32 v153, v46
	v_pk_mul_f32 v[62:63], v[152:153], v[62:63]
	v_mov_b32_e32 v154, v48
	v_mov_b32_e32 v155, v50
	v_cvt_pk_bf16_f32 v156, v62, v63
	v_pk_mul_f32 v[62:63], v[154:155], v[70:71]
	s_nop 0
	v_cvt_pk_bf16_f32 v157, v62, v63
	v_mov_b32_e32 v62, v52
	v_mov_b32_e32 v63, v54
	v_pk_mul_f32 v[70:71], v[62:63], v[118:119]
	s_nop 0
	v_cvt_pk_bf16_f32 v158, v70, v71
	v_mov_b32_e32 v70, v56
	v_mov_b32_e32 v71, v58
	v_pk_mul_f32 v[118:119], v[70:71], v[128:129]
	s_nop 0
	v_cvt_pk_bf16_f32 v159, v118, v119
	ds_write_b128 v66, v[156:159] offset:864
	s_and_b64 exec, exec, s[10:11]
	s_cbranch_execz .LBB0_798
	s_add_u32 s10, s22, s64
	v_lshl_or_b32 v172, v231, 10, v60
	s_addc_u32 s11, s23, s65
	v_mov_b32_e32 v64, v61
	v_mov_b32_e32 v68, v67
	v_lshl_add_u64 v[60:61], s[10:11], 0, v[172:173]
	v_pk_mul_f32 v[64:65], v[152:153], v[64:65]
	v_pk_mul_f32 v[66:67], v[154:155], v[68:69]
	v_mov_b32_e32 v74, v73
	v_mov_b32_e32 v134, v125
	v_add_co_u32_e32 v60, vcc, 0x16f8d000, v60
	v_cvt_pk_bf16_f32 v64, v64, v65
	v_cvt_pk_bf16_f32 v65, v66, v67
	v_pk_mul_f32 v[62:63], v[62:63], v[74:75]
	s_waitcnt lgkmcnt(8)
	v_pk_mul_f32 v[66:67], v[70:71], v[134:135]
	v_addc_co_u32_e32 v61, vcc, 0, v61, vcc
	v_cvt_pk_bf16_f32 v62, v62, v63
	v_cvt_pk_bf16_f32 v63, v66, v67
	v_swap_b32 v62, v64
	v_swap_b32 v63, v65
	s_nop 1
	v_permlane32_swap_b32_e32 v62, v64
	v_permlane32_swap_b32_e32 v63, v65
	v_lshl_add_u64 v[60:61], v[254:255], 0, v[60:61]
	global_store_dwordx4 v[60:61], v[62:65], off offset:1152
	s_nop 1

.LBB0_960:
	s_waitcnt lgkmcnt(0)
	v_mov_b32_e32 v48, s27
	s_movk_i32 s12, 0x90
	v_cvt_pk_bf16_f32 v44, v44, v45
	v_cvt_pk_bf16_f32 v45, v46, v47
	v_cvt_pk_bf16_f32 v46, v50, v51
	v_cvt_pk_bf16_f32 v47, v52, v53
	v_mad_u32_u24 v48, v230, s12, v48
	v_add_u32_e32 v143, 0, v100
	ds_write_b128 v48, v[44:47]
	v_add_u32_e32 v44, 0x17d00, v143
	ds_read_b128 v[44:47], v44
	v_lshl_add_u64 v[160:161], s[22:23], 0, v[102:103]
	s_mov_b32 s12, 0x16f91000
	v_add_co_u32_e32 v48, vcc, s12, v160
	v_or_b32_e32 v145, s18, v231
	s_nop 0
	v_addc_co_u32_e32 v49, vcc, 0, v161, vcc
	s_waitcnt lgkmcnt(0)
	global_store_dwordx4 v[48:49], v[44:47], off offset:256
	s_add_i32 s12, 0, 0x15900
	v_mul_u32_u24_e32 v52, 0x90, v231
	v_mul_u32_u24_e32 v44, 0x90, v145
	v_add3_u32 v147, s87, v139, v44
	v_add3_u32 v139, s12, v139, v52
	s_barrier
	ds_read_b128 v[44:47], v147
	ds_read_b128 v[48:51], v147 offset:2304
	ds_read_b128 v[52:55], v139
	ds_read_b128 v[60:63], v139 offset:2304
	s_waitcnt lgkmcnt(0)
	v_mfma_f32_16x16x32_bf16 v[64:67], v[60:63], v[44:47], 0
	s_mov_b64 s[12:13], -1
	s_and_b64 vcc, exec, s[10:11]
	v_mfma_f32_16x16x32_bf16 v[68:71], v[60:63], v[48:51], 0
	ds_read_b128 v[60:63], v139 offset:4608
	s_waitcnt lgkmcnt(0)
	v_mfma_f32_16x16x32_bf16 v[72:75], v[60:63], v[44:47], 0
	v_mfma_f32_16x16x32_bf16 v[162:165], v[60:63], v[48:51], 0
	ds_read_b128 v[60:63], v139 offset:6912
	v_mfma_f32_16x16x32_bf16 v[56:59], v[52:55], v[44:47], 0
	s_waitcnt lgkmcnt(0)
	v_mfma_f32_16x16x32_bf16 v[166:169], v[60:63], v[44:47], 0
	ds_read_b128 v[186:189], v147 offset:64
	ds_read_b128 v[190:193], v147 offset:2368
	ds_read_b128 v[44:47], v139 offset:64
	v_mfma_f32_16x16x32_bf16 v[52:55], v[52:55], v[48:51], 0
	v_mfma_f32_16x16x32_bf16 v[182:185], v[60:63], v[48:51], 0
	s_waitcnt lgkmcnt(0)
	v_mfma_f32_16x16x32_bf16 v[48:51], v[44:47], v[186:189], v[56:59]
	v_mfma_f32_16x16x32_bf16 v[44:47], v[44:47], v[190:193], v[52:55]
	s_nop 1
	ds_read_b128 v[56:59], v139 offset:4672
	s_nop 0
	ds_read_b128 v[52:55], v139 offset:2368
	s_waitcnt lgkmcnt(0)
	v_mfma_f32_16x16x32_bf16 v[60:63], v[52:55], v[186:189], v[64:67]
	v_mfma_f32_16x16x32_bf16 v[52:55], v[52:55], v[190:193], v[68:71]
	s_nop 2
	ds_read_b128 v[68:71], v139 offset:6976
	v_mfma_f32_16x16x32_bf16 v[64:67], v[56:59], v[186:189], v[72:75]
	v_mfma_f32_16x16x32_bf16 v[56:59], v[56:59], v[190:193], v[162:165]
	s_waitcnt lgkmcnt(0)
	v_mfma_f32_16x16x32_bf16 v[72:75], v[68:71], v[186:189], v[166:169]
	v_mfma_f32_16x16x32_bf16 v[68:71], v[68:71], v[190:193], v[182:185]
	s_cbranch_vccnz .LBB0_962
	v_lshlrev_b32_e32 v139, 7, v145
	s_add_u32 s10, s22, s64
	v_and_or_b32 v172, v101, 48, v139
	s_addc_u32 s11, s23, s65
	v_lshl_add_u64 v[164:165], s[10:11], 0, v[172:173]
	s_mov_b32 s10, 0x16f7d000
	v_add_co_u32_e32 v164, vcc, s10, v164
	v_cvt_pk_bf16_f32 v48, v48, v49
	v_cvt_pk_bf16_f32 v49, v50, v51
	v_addc_co_u32_e32 v165, vcc, 0, v165, vcc
	v_cvt_pk_bf16_f32 v44, v44, v45
	v_cvt_pk_bf16_f32 v45, v46, v47
	v_cvt_pk_bf16_f32 v50, v60, v61
	v_cvt_pk_bf16_f32 v51, v62, v63
	v_cvt_pk_bf16_f32 v46, v52, v53
	v_cvt_pk_bf16_f32 v47, v54, v55
	v_cvt_pk_bf16_f32 v64, v64, v65
	v_cvt_pk_bf16_f32 v65, v66, v67
	v_cvt_pk_bf16_f32 v56, v56, v57
	v_cvt_pk_bf16_f32 v57, v58, v59
	v_cvt_pk_bf16_f32 v66, v72, v73
	v_cvt_pk_bf16_f32 v67, v74, v75
	v_cvt_pk_bf16_f32 v58, v68, v69
	v_cvt_pk_bf16_f32 v59, v70, v71
	s_nop 1
	v_permlane32_swap_b32_e32 v48, v50
	v_permlane32_swap_b32_e32 v49, v51
	v_permlane32_swap_b32_e32 v44, v46
	v_permlane32_swap_b32_e32 v45, v47
	v_permlane32_swap_b32_e32 v64, v66
	v_permlane32_swap_b32_e32 v65, v67
	v_permlane32_swap_b32_e32 v56, v58
	v_permlane32_swap_b32_e32 v57, v59
	s_nop 1
	v_permlane16_swap_b32_e32 v48, v50
	v_permlane16_swap_b32_e32 v49, v51
	v_permlane16_swap_b32_e32 v44, v46
	v_permlane16_swap_b32_e32 v45, v47
	v_permlane16_swap_b32_e32 v64, v66
	v_permlane16_swap_b32_e32 v65, v67
	v_permlane16_swap_b32_e32 v56, v58
	v_permlane16_swap_b32_e32 v57, v59
	s_nop 1
	global_store_dwordx4 v[164:165], v[48:51], off offset:256
	global_store_dwordx4 v[164:165], v[64:67], off offset:320
	global_store_dwordx4 v[164:165], v[44:47], off offset:2304
	global_store_dwordx4 v[164:165], v[56:59], off offset:2368
	s_mov_b64 s[12:13], 0
